# banded-attention unit prologue: sink value wait deferred past the K/V DMA issue
# speedup vs baseline: 1.0054x; 1.0054x over previous
.LBB0_364:
	s_mul_hi_i32 s1, s0, 0x66666667
	s_lshr_b32 s4, s1, 31
	s_ashr_i32 s1, s1, 10
	s_add_i32 s1, s1, s4
	s_mulk_i32 s1, 0xa00
	s_sub_i32 s1, s0, s1
	s_cmpk_gt_i32 s1, 0x3ff
	s_cselect_b64 s[16:17], -1, 0
	s_and_b64 vcc, exec, s[16:17]
	s_cbranch_vccnz .LBB0_367
	s_lshr_b32 s5, s1, 2
	s_bfe_u32 s4, s1, 0x30006
	s_and_b32 s5, s5, 64
	s_lshl_b32 s14, s4, 6
	s_or_b32 s7, s5, 0x200
	s_or_b32 s48, s5, 0x280
	s_lshl_b32 s5, s4, 7
	v_readlane_b32 s8, v250, 53
	v_readlane_b32 s9, v250, 54
	s_add_u32 s44, s8, s5
	v_readlane_b32 s5, v251, 44
	v_readlane_b32 s52, v252, 0
	s_mov_b64 s[38:39], s[14:15]
	s_addc_u32 s45, s9, 0
	s_or_b32 s14, s4, s5
	v_readlane_b32 s56, v252, 4
	v_readlane_b32 s57, v252, 5
	v_readlane_b32 s64, v252, 12
	v_readlane_b32 s65, v252, 13
	s_lshl_b64 s[30:31], s[14:15], 2
	s_mov_b64 s[56:57], s[64:65]
	s_add_u32 s30, s56, s30
	s_addc_u32 s31, s57, s31
	global_load_dword v183, v1, s[30:31]
	v_readlane_b32 s66, v252, 14
	v_readlane_b32 s67, v252, 15
	v_readlane_b32 s66, v251, 21
	s_lshl_b32 s5, s1, 5
	s_lshl_b32 s8, s1, 8
	v_readlane_b32 s67, v251, 22
	s_and_b32 s36, s5, 0xffffc000
	s_and_b32 s30, s8, 0x3f00
	s_mov_b32 s14, s7
	v_readlane_b32 s53, v252, 1
	v_readlane_b32 s54, v252, 2
	v_readlane_b32 s55, v252, 3
	v_readlane_b32 s58, v252, 6
	v_readlane_b32 s59, v252, 7
	v_readlane_b32 s60, v252, 8
	v_readlane_b32 s61, v252, 9
	v_readlane_b32 s62, v252, 10
	v_readlane_b32 s63, v252, 11
	s_mov_b32 s5, 1
	s_cbranch_execz .LBB0_368
	s_mov_b64 s[46:47], 0x300
	s_mov_b64 s[40:41], 0
	s_movk_i32 s13, 0xff81
	s_mov_b64 s[42:43], 0
	s_branch .LBB0_369

.LBB0_398:
	s_waitcnt vmcnt(6)
	ds_write_b32 v15, v3
	s_and_b64 vcc, exec, s[16:17]
	s_cbranch_vccnz .Le2_nosink
	v_mul_f32_e32 v140, 0x3fb8aa3b, v183
